# GLA S-update: K^T/V^T operand fragments (8 ds_read_b128) prefetched into idle VGPRs right after the third barrier; MFMA chain no longer waits per read
# baseline (speedup 1.0000x reference)
; __device__ __forceinline__ bf16_t f2bf(float f) { return (bf16_t)(cvt_pk_bf16(f, 0.f) & 0xffffu); }
; #define MFMA16(a, b, c) __builtin_amdgcn_mfma_f32_16x16x32_bf16((a), (b), (c), 0, 0, 0)
; __device__ __forceinline__ void gla_unit(const Params& p, const WS& ws, int u, bool dry = false) {
;     ...
; #pragma unroll
;     for (int ks = 0; ks < 4; ++ks)
; #pragma unroll
;       for (int mt = 0; mt < 2; ++mt) {
;         const bf16x8 sf = *(const bf16x8*)(STs + (16 * mt + lr) * 136 + 32 * ks + 8 * lq);
;         oacc[mt] = MFMA16(sf, xq[ks], oacc[mt]);
;       }
;     {
;       const int t = 64 * c - 48 + irow;
;       float sq = 0.f;
; #pragma unroll
;       for (int mt = 0; mt < 2; ++mt) sq += oacc[mt][0] * oacc[mt][0] + oacc[mt][1] * oacc[mt][1] + oacc[mt][2] * oacc[mt][2] + oacc[mt][3] * oacc[mt][3];
;       sq += __shfl_xor(sq, 16); sq += __shfl_xor(sq, 32);
;       tpend = t;
;       sqpend = sq;
; #pragma unroll
;       for (int mt = 0; mt < 2; ++mt) { opend[mt].x = cvt_pk_bf16(oacc[mt][0], oacc[mt][1]); opend[mt].y = cvt_pk_bf16(oacc[mt][2], oacc[mt][3]); }
;     }
;     __syncthreads();
; #pragma unroll
;     for (int ntl = 0; ntl < 2; ++ntl) {
; #pragma unroll
;       for (int ks = 0; ks < 2; ++ks) {
;         const bf16x8 kf = *(const bf16x8*)(KIT + (16 * (2 * w + ntl) + lr) * 72 + (((4 * ks + lq) ^ (((16 * (2 * w + ntl) + lr) >> 3) & 7)) << 3));
; #pragma unroll
;         for (int mt = 0; mt < 2; ++mt) {
;           const bf16x8 vf = *(const bf16x8*)(VTs + (16 * mt + lr) * 72 + (((4 * ks + lq) ^ (((16 * mt + lr) >> 3) & 3)) << 3));
;           sacc[mt][ntl] = MFMA16(vf, kf, sacc[mt][ntl]);
;         }
;       }
;       const float e = ntl ? eb1 : eb0;
; #pragma unroll
;       for (int mt = 0; mt < 2; ++mt) {
;         sacc[mt][ntl] = scale4(sacc[mt][ntl], e);
; #pragma unroll
;         for (int jj = 0; jj < 4; ++jj) STs[(16 * mt + 4 * lq + jj) * 136 + 16 * (2 * w + ntl) + lr] = f2bf(sacc[mt][ntl][jj]);
;       }
;     }
.LBB0_1634:
	s_or_b64 exec, exec, s[12:13]
	s_nop 1
	s_nop 0
	s_nop 0
	s_cmp_gt_u32 s35, 32
	s_waitcnt lgkmcnt(0)
	v_mfma_f32_16x16x32_bf16 v[108:111], v[212:215], v[104:107], v[116:119]
	s_waitcnt lgkmcnt(0)
	v_mfma_f32_16x16x32_bf16 v[104:107], v[216:219], v[104:107], v[120:123]
	s_nop 0
	s_waitcnt lgkmcnt(0)
	v_mfma_f32_16x16x32_bf16 v[108:111], v[220:223], v[100:103], v[108:111]
	s_nop 0
	s_waitcnt lgkmcnt(0)
	v_mfma_f32_16x16x32_bf16 v[100:103], v[224:227], v[100:103], v[104:107]
	s_nop 2
	s_nop 0
	s_waitcnt lgkmcnt(0)
	v_mfma_f32_16x16x32_bf16 v[104:107], v[228:231], v[8:11], v[108:111]
	s_nop 2
	s_nop 0
	s_waitcnt lgkmcnt(0)
	v_mfma_f32_16x16x32_bf16 v[8:11], v[232:235], v[8:11], v[100:103]
	s_nop 2
	s_nop 0
	s_waitcnt lgkmcnt(0)
	v_mfma_f32_16x16x32_bf16 v[100:103], v[244:247], v[4:7], v[104:107]
	s_nop 2
	s_nop 0
	s_waitcnt lgkmcnt(0)
	s_barrier
	v_mfma_f32_16x16x32_bf16 v[6:9], v[248:251], v[4:7], v[8:11]
	ds_read_b128 v[212:215], v169 offset:34816
	ds_read_b128 v[216:219], v170 offset:53248
	ds_read_b128 v[220:223], v171 offset:53248
	ds_read_b128 v[224:227], v172 offset:34816
	ds_read_b128 v[228:231], v173 offset:53248
	ds_read_b128 v[232:235], v174 offset:53248
	ds_read_b128 v[244:247], v180 offset:34816
	ds_read_b128 v[252:255], v181 offset:34816
	s_nop 2
	v_mov_b32_e32 v10, v101
	v_mov_b32_e32 v4, v100
	s_nop 2
	v_mov_b32_e32 v11, v7
	v_mov_b32_e32 v5, v6
	v_pk_mul_f32 v[10:11], v[10:11], v[10:11]
	v_cvt_pk_bf16_f32 v6, v6, v7
	v_pk_fma_f32 v[4:5], v[4:5], v[4:5], v[10:11]
	v_mov_b32_e32 v10, v102
	v_mov_b32_e32 v11, v8
	v_pk_fma_f32 v[4:5], v[10:11], v[10:11], v[4:5]
	v_mov_b32_e32 v10, v103
	v_mov_b32_e32 v11, v9
	v_pk_fma_f32 v[4:5], v[10:11], v[10:11], v[4:5]
	v_cvt_pk_bf16_f32 v7, v8, v9
	v_add_f32_e32 v4, v4, v5
	ds_bpermute_b32 v5, v163, v4
	v_mov_b32_e32 v8, v208
	s_waitcnt lgkmcnt(0)
	v_add_f32_e32 v4, v4, v5
	ds_bpermute_b32 v5, v168, v4
	s_waitcnt lgkmcnt(0)
	v_add_f32_e32 v10, v4, v5
	v_cvt_pk_bf16_f32 v4, v100, v101
	v_cvt_pk_bf16_f32 v5, v102, v103
	s_nop 0
	s_nop 0
	s_waitcnt lgkmcnt(0)
	v_mfma_f32_16x16x32_bf16 v[84:87], v[216:219], v[212:215], v[84:87]
	s_nop 0
	s_nop 0
	v_mfma_f32_16x16x32_bf16 v[96:99], v[220:223], v[212:215], v[96:99]
	s_nop 0
	s_nop 0
	s_nop 0
	v_mfma_f32_16x16x32_bf16 v[84:87], v[228:231], v[224:227], v[84:87]
	s_nop 0
	s_nop 0
	v_mfma_f32_16x16x32_bf16 v[96:99], v[232:235], v[224:227], v[96:99]
	s_nop 4
	v_mul_f32_e32 v84, v84, v8
	v_mul_f32_e32 v85, v85, v8
	v_mul_f32_e32 v86, v86, v8
	v_mul_f32_e32 v87, v87, v8
	s_nop 0
	v_cvt_pk_bf16_f32 v8, v84, s0
	ds_write_b16 v178, v8 offset:57856
	v_cvt_pk_bf16_f32 v8, v85, s0
	ds_write_b16 v178, v8 offset:58128
	v_cvt_pk_bf16_f32 v8, v86, s0
	ds_write_b16 v178, v8 offset:58400
	v_cvt_pk_bf16_f32 v8, v87, s0
	ds_write_b16 v178, v8 offset:58672
	s_nop 0
	v_mul_f32_e32 v96, v96, v208
	v_mul_f32_e32 v97, v97, v208
	v_mul_f32_e32 v98, v98, v208
	v_mul_f32_e32 v99, v99, v208
	s_nop 0
	v_cvt_pk_bf16_f32 v8, v96, s0
	ds_write_b16 v178, v8 offset:62208
	v_cvt_pk_bf16_f32 v8, v97, s0
	ds_write_b16 v178, v8 offset:62480
	v_cvt_pk_bf16_f32 v8, v98, s0
	ds_write_b16 v178, v8 offset:62752
	v_cvt_pk_bf16_f32 v8, v99, s0
	ds_write_b16 v178, v8 offset:63024
	s_nop 0
	s_nop 0
	s_nop 0
	v_mfma_f32_16x16x32_bf16 v[88:91], v[216:219], v[244:247], v[88:91]
	s_nop 0
	v_mov_b32_e32 v8, v207
	s_nop 0
	v_mfma_f32_16x16x32_bf16 v[92:95], v[220:223], v[244:247], v[92:95]
	s_nop 0
	s_nop 0
	s_nop 0
	v_mfma_f32_16x16x32_bf16 v[88:91], v[228:231], v[252:255], v[88:91]
	s_nop 0
	s_nop 0
	v_mfma_f32_16x16x32_bf16 v[92:95], v[232:235], v[252:255], v[92:95]
	s_nop 4
	v_mul_f32_e32 v88, v88, v8
	v_mul_f32_e32 v89, v89, v8
	v_mul_f32_e32 v90, v90, v8
	v_mul_f32_e32 v91, v91, v8
	s_nop 0
	v_cvt_pk_bf16_f32 v8, v88, s0
	ds_write_b16 v178, v8 offset:57888
	v_cvt_pk_bf16_f32 v8, v89, s0
	ds_write_b16 v178, v8 offset:58160
	v_cvt_pk_bf16_f32 v8, v90, s0
	ds_write_b16 v178, v8 offset:58432
	v_cvt_pk_bf16_f32 v8, v91, s0
	ds_write_b16 v178, v8 offset:58704
	s_nop 0
	v_mul_f32_e32 v92, v92, v207
	v_mul_f32_e32 v93, v93, v207
	v_mul_f32_e32 v94, v94, v207
	v_mul_f32_e32 v95, v95, v207
	s_nop 0
	v_cvt_pk_bf16_f32 v8, v92, s0
	ds_write_b16 v178, v8 offset:62240
	v_cvt_pk_bf16_f32 v8, v93, s0
	ds_write_b16 v178, v8 offset:62512
	v_cvt_pk_bf16_f32 v8, v94, s0
	ds_write_b16 v178, v8 offset:62784
	v_cvt_pk_bf16_f32 v8, v95, s0
	ds_write_b16 v178, v8 offset:63056
	s_waitcnt lgkmcnt(0)
	s_barrier
	s_cbranch_scc1 .LBB0_1663
	v_add_u32_e32 v207, s92, v161
	v_subrev_u32_e32 v8, 48, v207
	v_cmp_lt_i32_e64 s[80:81], -1, v8
	ds_write_b128 v147, v[44:47]
	ds_write_b128 v147, v[48:51] offset:17408
	ds_write_b16 v148, v48 offset:34816
	ds_write_b16_d16_hi v149, v48 offset:34960
	ds_write_b16 v148, v49 offset:35104
	ds_write_b16_d16_hi v148, v49 offset:35248
	ds_write_b16 v148, v50 offset:35392
	ds_write_b16_d16_hi v148, v50 offset:35536
	ds_write_b16 v148, v51 offset:35680
	ds_write_b16_d16_hi v148, v51 offset:35824
	ds_write_b128 v150, v[56:59]
	ds_write_b128 v150, v[52:55] offset:17408
	ds_write_b16 v151, v52 offset:34816
	ds_write_b16_d16_hi v152, v52 offset:34960
	ds_write_b16 v151, v53 offset:35104
	ds_write_b16_d16_hi v151, v53 offset:35248
	ds_write_b16 v151, v54 offset:35392
	ds_write_b16_d16_hi v151, v54 offset:35536
	ds_write_b16 v151, v55 offset:35680
	ds_write_b16_d16_hi v151, v55 offset:35824
	ds_write_b128 v153, v[64:67]
	ds_write_b128 v153, v[68:71] offset:17408
	ds_write_b16 v154, v68 offset:34816
	ds_write_b16_d16_hi v155, v68 offset:34960
	ds_write_b16 v154, v69 offset:35104
	ds_write_b16_d16_hi v154, v69 offset:35248
	ds_write_b16 v154, v70 offset:35392
	ds_write_b16_d16_hi v154, v70 offset:35536
	ds_write_b16 v154, v71 offset:35680
	ds_write_b16_d16_hi v154, v71 offset:35824
	ds_write_b128 v156, v[72:75]
	ds_write_b128 v156, v[76:79] offset:17408
	ds_write_b16 v157, v76 offset:34816
	ds_write_b16_d16_hi v158, v76 offset:34960
	ds_write_b16 v157, v77 offset:35104
	ds_write_b16_d16_hi v157, v77 offset:35248
	ds_write_b16 v157, v78 offset:35392
	ds_write_b16_d16_hi v157, v78 offset:35536
	ds_write_b16 v157, v79 offset:35680
	ds_write_b16_d16_hi v157, v79 offset:35824
	ds_write_b16 v159, v80 offset:53248
	ds_write_b16_d16_hi v160, v80 offset:53392
	ds_write_b16 v159, v81 offset:53536
	ds_write_b16_d16_hi v159, v81 offset:53680
	ds_write_b16 v159, v82 offset:53824
	ds_write_b16_d16_hi v159, v82 offset:53968
	ds_write_b16 v159, v83 offset:54112
	ds_write_b16_d16_hi v159, v83 offset:54256
	s_waitcnt lgkmcnt(0)
	s_barrier
	s_and_saveexec_b64 s[12:13], s[80:81]
	s_cbranch_execz .LBB0_1638
	v_add_u32_e32 v8, s92, v203
	v_ashrrev_i32_e32 v9, 31, v8
	v_lshlrev_b64 v[14:15], 11, v[8:9]
	v_lshl_add_u64 v[14:15], v[138:139], 0, v[14:15]
	global_store_dwordx2 v[14:15], v[4:5], off
	global_store_dwordx2 v[14:15], v[6:7], off offset:32
	s_and_b64 exec, exec, s[44:45]
	s_cbranch_execz .LBB0_1638
	v_lshlrev_b64 v[4:5], 7, v[8:9]
	v_lshl_add_u64 v[4:5], s[6:7], 0, v[4:5]
	global_store_dword v[4:5], v10, off

; __device__ __forceinline__ bf16_t f2bf(float f) { return (bf16_t)(cvt_pk_bf16(f, 0.f) & 0xffffu); }
; #define MFMA16(a, b, c) __builtin_amdgcn_mfma_f32_16x16x32_bf16((a), (b), (c), 0, 0, 0)
; __device__ __forceinline__ void gla_unit(const Params& p, const WS& ws, int u, bool dry = false) {
;     ...
; #pragma unroll
;     for (int ks = 0; ks < 4; ++ks)
; #pragma unroll
;       for (int mt = 0; mt < 2; ++mt) {
;         const bf16x8 sf = *(const bf16x8*)(STs + (16 * mt + lr) * 136 + 32 * ks + 8 * lq);
;         oacc[mt] = MFMA16(sf, xq[ks], oacc[mt]);
;       }
;     {
;       const int t = 64 * c - 48 + irow;
;       float sq = 0.f;
; #pragma unroll
;       for (int mt = 0; mt < 2; ++mt) sq += oacc[mt][0] * oacc[mt][0] + oacc[mt][1] * oacc[mt][1] + oacc[mt][2] * oacc[mt][2] + oacc[mt][3] * oacc[mt][3];
;       sq += __shfl_xor(sq, 16); sq += __shfl_xor(sq, 32);
;       tpend = t;
;       sqpend = sq;
; #pragma unroll
;       for (int mt = 0; mt < 2; ++mt) { opend[mt].x = cvt_pk_bf16(oacc[mt][0], oacc[mt][1]); opend[mt].y = cvt_pk_bf16(oacc[mt][2], oacc[mt][3]); }
;     }
;     __syncthreads();
; #pragma unroll
;     for (int ntl = 0; ntl < 2; ++ntl) {
; #pragma unroll
;       for (int ks = 0; ks < 2; ++ks) {
;         const bf16x8 kf = *(const bf16x8*)(KIT + (16 * (2 * w + ntl) + lr) * 72 + (((4 * ks + lq) ^ (((16 * (2 * w + ntl) + lr) >> 3) & 7)) << 3));
; #pragma unroll
;         for (int mt = 0; mt < 2; ++mt) {
;           const bf16x8 vf = *(const bf16x8*)(VTs + (16 * mt + lr) * 72 + (((4 * ks + lq) ^ (((16 * mt + lr) >> 3) & 3)) << 3));
;           sacc[mt][ntl] = MFMA16(vf, kf, sacc[mt][ntl]);
;         }
;       }
;       const float e = ntl ? eb1 : eb0;
; #pragma unroll
;       for (int mt = 0; mt < 2; ++mt) {
;         sacc[mt][ntl] = scale4(sacc[mt][ntl], e);
; #pragma unroll
;         for (int jj = 0; jj < 4; ++jj) STs[(16 * mt + 4 * lq + jj) * 136 + 16 * (2 * w + ntl) + lr] = f2bf(sacc[mt][ntl][jj]);
;       }
;     }
;     __syncthreads();
.LBB0_1662:
	s_or_b64 exec, exec, s[12:13]
	s_nop 1
	s_nop 0
	s_nop 0
	s_waitcnt lgkmcnt(0)
	v_mfma_f32_16x16x32_bf16 v[108:111], v[212:215], v[104:107], v[116:119]
	s_waitcnt lgkmcnt(0)
	v_mfma_f32_16x16x32_bf16 v[104:107], v[216:219], v[104:107], v[120:123]
	s_nop 0
	s_waitcnt lgkmcnt(0)
	v_mfma_f32_16x16x32_bf16 v[108:111], v[220:223], v[100:103], v[108:111]
	s_nop 0
	s_waitcnt lgkmcnt(0)
	v_mfma_f32_16x16x32_bf16 v[100:103], v[224:227], v[100:103], v[104:107]
	s_nop 2
	s_nop 0
	s_waitcnt lgkmcnt(0)
	v_mfma_f32_16x16x32_bf16 v[104:107], v[228:231], v[8:11], v[108:111]
	s_nop 2
	s_nop 0
	s_waitcnt lgkmcnt(0)
	v_mfma_f32_16x16x32_bf16 v[8:11], v[232:235], v[8:11], v[100:103]
	s_nop 2
	s_nop 0
	s_waitcnt lgkmcnt(0)
	v_mfma_f32_16x16x32_bf16 v[100:103], v[244:247], v[4:7], v[104:107]
	s_nop 2
	s_nop 0
	s_waitcnt lgkmcnt(0)
	s_barrier
	v_mfma_f32_16x16x32_bf16 v[6:9], v[248:251], v[4:7], v[8:11]
	ds_read_b128 v[212:215], v169 offset:34816
	ds_read_b128 v[216:219], v170 offset:53248
	ds_read_b128 v[220:223], v171 offset:53248
	ds_read_b128 v[224:227], v172 offset:34816
	ds_read_b128 v[228:231], v173 offset:53248
	ds_read_b128 v[232:235], v174 offset:53248
	ds_read_b128 v[244:247], v180 offset:34816
	ds_read_b128 v[252:255], v181 offset:34816
	s_nop 2
	v_mov_b32_e32 v10, v101
	v_mov_b32_e32 v4, v100
	s_nop 2
	v_mov_b32_e32 v11, v7
	v_mov_b32_e32 v5, v6
	v_pk_mul_f32 v[10:11], v[10:11], v[10:11]
	v_cvt_pk_bf16_f32 v6, v6, v7
	v_pk_fma_f32 v[4:5], v[4:5], v[4:5], v[10:11]
	v_mov_b32_e32 v10, v102
	v_mov_b32_e32 v11, v8
	v_pk_fma_f32 v[4:5], v[10:11], v[10:11], v[4:5]
	v_mov_b32_e32 v10, v103
	v_mov_b32_e32 v11, v9
	v_pk_fma_f32 v[4:5], v[10:11], v[10:11], v[4:5]
	v_cvt_pk_bf16_f32 v7, v8, v9
	v_add_f32_e32 v4, v4, v5
	ds_bpermute_b32 v5, v163, v4
	v_mov_b32_e32 v8, v204
	v_add_u32_e32 v11, 16, v207
	s_waitcnt lgkmcnt(0)
	v_add_f32_e32 v4, v4, v5
	ds_bpermute_b32 v5, v168, v4
	s_waitcnt lgkmcnt(0)
	v_add_f32_e32 v10, v4, v5
	v_cvt_pk_bf16_f32 v4, v100, v101
	v_cvt_pk_bf16_f32 v5, v102, v103
	s_nop 0
	s_nop 0
	s_waitcnt lgkmcnt(0)
	v_mfma_f32_16x16x32_bf16 v[84:87], v[216:219], v[212:215], v[84:87]
	s_nop 0
	s_nop 0
	v_mfma_f32_16x16x32_bf16 v[96:99], v[220:223], v[212:215], v[96:99]
	s_nop 0
	s_nop 0
	s_nop 0
	v_mfma_f32_16x16x32_bf16 v[84:87], v[228:231], v[224:227], v[84:87]
	s_nop 0
	s_nop 0
	v_mfma_f32_16x16x32_bf16 v[96:99], v[232:235], v[224:227], v[96:99]
	s_nop 4
	v_mul_f32_e32 v84, v84, v8
	v_mul_f32_e32 v85, v85, v8
	v_mul_f32_e32 v86, v86, v8
	v_mul_f32_e32 v87, v87, v8
	s_nop 0
	v_cvt_pk_bf16_f32 v8, v84, s0
	ds_write_b16 v178, v8 offset:57856
	v_cvt_pk_bf16_f32 v8, v85, s0
	ds_write_b16 v178, v8 offset:58128
	v_cvt_pk_bf16_f32 v8, v86, s0
	ds_write_b16 v178, v8 offset:58400
	v_cvt_pk_bf16_f32 v8, v87, s0
	ds_write_b16 v178, v8 offset:58672
	s_nop 0
	v_mul_f32_e32 v96, v96, v204
	v_mul_f32_e32 v97, v97, v204
	v_mul_f32_e32 v98, v98, v204
	v_mul_f32_e32 v99, v99, v204
	s_nop 0
	v_cvt_pk_bf16_f32 v8, v96, s0
	ds_write_b16 v178, v8 offset:62208
	v_cvt_pk_bf16_f32 v8, v97, s0
	ds_write_b16 v178, v8 offset:62480
	v_cvt_pk_bf16_f32 v8, v98, s0
	ds_write_b16 v178, v8 offset:62752
	v_cvt_pk_bf16_f32 v8, v99, s0
	ds_write_b16 v178, v8 offset:63024
	s_nop 0
	s_nop 0
	s_nop 0
	v_mfma_f32_16x16x32_bf16 v[88:91], v[216:219], v[244:247], v[88:91]
	s_nop 0
	v_mov_b32_e32 v8, v179
	s_nop 0
	v_mfma_f32_16x16x32_bf16 v[92:95], v[220:223], v[244:247], v[92:95]
	s_nop 0
	s_nop 0
	s_nop 0
	v_mfma_f32_16x16x32_bf16 v[88:91], v[228:231], v[252:255], v[88:91]
	s_nop 0
	s_nop 0
	v_mfma_f32_16x16x32_bf16 v[92:95], v[232:235], v[252:255], v[92:95]
	s_nop 4
	v_mul_f32_e32 v88, v88, v8
	v_mul_f32_e32 v89, v89, v8
	v_mul_f32_e32 v90, v90, v8
	v_mul_f32_e32 v91, v91, v8
	s_nop 0
	v_cvt_pk_bf16_f32 v8, v88, s0
	ds_write_b16 v178, v8 offset:57888
	v_cvt_pk_bf16_f32 v8, v89, s0
	ds_write_b16 v178, v8 offset:58160
	v_cvt_pk_bf16_f32 v8, v90, s0
	ds_write_b16 v178, v8 offset:58432
	v_cvt_pk_bf16_f32 v8, v91, s0
	ds_write_b16 v178, v8 offset:58704
	s_nop 0
	v_mul_f32_e32 v92, v92, v179
	v_mul_f32_e32 v93, v93, v179
	v_mul_f32_e32 v94, v94, v179
	v_mul_f32_e32 v95, v95, v179
	s_nop 0
	v_cvt_pk_bf16_f32 v8, v92, s0
	ds_write_b16 v178, v8 offset:62240
	v_cvt_pk_bf16_f32 v8, v93, s0
	ds_write_b16 v178, v8 offset:62512
	v_cvt_pk_bf16_f32 v8, v94, s0
	ds_write_b16 v178, v8 offset:62784
	v_cvt_pk_bf16_f32 v8, v95, s0
	ds_write_b16 v178, v8 offset:63056
	s_waitcnt lgkmcnt(0)
	s_barrier
	s_branch .LBB0_1664
